# R2/R3 fast bodies: iteration head computes only the x pointers; modulation row pointers are computed on the cold entry only (the prefetching middle already has them)
# speedup vs baseline: 1.0227x; 1.0040x over previous
;     __device__ __forceinline__ void init(int N, int G, int c, int latent_only) { lat = latent_only; b.init(latent_only ? NB * SEQ : M, N, G, c); }
;     __device__ __forceinline__ void init(int c_, unsigned* cnt_) { lat.init(NB * SEQ, FF2, 1, 0); c = c_; cnt = cnt_; }
; __device__ __forceinline__ void row_pass(const RowPass& R, int gw, int ngw, int lane) {
;     ...
;     for (int row0 = gw; row0 < M; row0 += NR * ngw) {
;         f32x4 v[NR][4]; u32x2 yw[NR][4]; bool act[NR]; float* xrow[NR]; int bbs[NR];
; #pragma unroll
;         for (int k = 0; k < NR; ++k) {
;             const int row = row0 + k * ngw;
;             const int rowc = row < M ? row : row0;
;             const int b = rowc / RPB, i = rowc - b * RPB; const bool isctx = i < CTXL;
;             act[k] = (row < M) && !(isctx && R.skip_ctx);
;             bbs[k] = isctx ? 8 : b;
;             xrow[k] = isctx ? R.xc + ((size_t)b * CTXL + i) * DM : R.out + ((size_t)b * SEQ + (i - CTXL)) * DM;
;             const float* src = R.init ? (isctx ? R.ctx_in + ((size_t)b * CTXL + i) * DM : R.x_in + ((size_t)b * SEQ + (i - CTXL)) * DM) : xrow[k];
;             if (act[k]) {
; #pragma unroll
;                 for (int j = 0; j < 4; ++j) v[k][j] = __builtin_nontemporal_load((const f32x4*)(src + lane * 4 + 256 * j));
;                 if (R.update) { const bf16* yr = R.Y + (size_t)rowc * DM;
; #pragma unroll
;                     for (int j = 0; j < 4; ++j) yw[k][j] = __builtin_nontemporal_load((const u32x2*)(yr + lane * 4 + 256 * j)); }
;             }
.LBB0_132:
	s_mul_hi_i32 s6, s13, 0x78787879
	s_lshr_b32 s7, s6, 31
	s_ashr_i32 s6, s6, 11
	s_add_i32 s6, s6, s7
	s_mul_i32 s7, s6, 0xffffef00
	s_add_i32 s7, s13, s7
	s_cmpk_gt_i32 s7, 0xff
	s_cselect_b64 s[50:51], -1, 0
	s_add_i32 s8, s44, s13
	s_cmp_lt_i32 s8, 0x8800
	s_cbranch_scc0 .Lr2_slow
	s_mul_hi_i32 s9, s8, 0x78787879
	s_lshr_b32 s25, s9, 31
	s_ashr_i32 s9, s9, 11
	s_add_i32 s9, s9, s25
	s_mul_i32 s25, s9, 0xffffef00
	s_add_i32 s25, s8, s25
	s_cmpk_gt_i32 s25, 0xff
	s_cselect_b64 s[52:53], -1, 0
	s_and_b64 s[46:47], s[50:51], s[52:53]
	s_or_b64 s[46:47], s[46:47], s[62:63]
	s_cmp_lg_u64 s[46:47], 0
	s_cbranch_scc0 .Lr2_slow
	v_lshlrev_b32_e32 v160, 2, v36
	s_add_i32 s72, s7, 0xffffff00
	s_cmp_lg_u64 s[50:51], 0
	s_cselect_b32 s27, s4, s49
	s_cselect_b32 s32, s5, s55
	s_cselect_b32 s37, 24, 20
	s_cselect_b32 s72, s72, s7
	s_mov_b32 s40, s6
	s_mov_b32 s41, 0
	s_lshl_b64 s[40:41], s[40:41], s37
	s_add_u32 s40, s27, s40
	s_addc_u32 s41, s32, s41
	s_lshl_b32 s72, s72, 12
	s_add_u32 s40, s40, s72
	s_addc_u32 s41, s41, 0
	s_cmp_eq_u32 s12, 0
	s_cbranch_scc1 .Lr2_slow_keepd
	s_mov_b64 s[68:69], 0
	s_mov_b64 s[70:71], 0

;     __device__ __forceinline__ void init(int c_, unsigned* cnt_) { lat.init(NB * SEQ, FF2, 1, 0); c = c_; cnt = cnt_; }
; __device__ __forceinline__ void row_pass(const RowPass& R, int gw, int ngw, int lane) {
;     ...
;     for (int row0 = gw; row0 < M; row0 += NR * ngw) {
;         f32x4 v[NR][4]; u32x2 yw[NR][4]; bool act[NR]; float* xrow[NR]; int bbs[NR];
; #pragma unroll
;         for (int k = 0; k < NR; ++k) {
;             const int row = row0 + k * ngw;
;             const int rowc = row < M ? row : row0;
;             const int b = rowc / RPB, i = rowc - b * RPB; const bool isctx = i < CTXL;
;             act[k] = (row < M) && !(isctx && R.skip_ctx);
;             bbs[k] = isctx ? 8 : b;
;             xrow[k] = isctx ? R.xc + ((size_t)b * CTXL + i) * DM : R.out + ((size_t)b * SEQ + (i - CTXL)) * DM;
;             const float* src = R.init ? (isctx ? R.ctx_in + ((size_t)b * CTXL + i) * DM : R.x_in + ((size_t)b * SEQ + (i - CTXL)) * DM) : xrow[k];
;             if (act[k]) {
; #pragma unroll
;                 for (int j = 0; j < 4; ++j) v[k][j] = __builtin_nontemporal_load((const f32x4*)(src + lane * 4 + 256 * j));
;                 if (R.update) { const bf16* yr = R.Y + (size_t)rowc * DM;
; #pragma unroll
;                     for (int j = 0; j < 4; ++j) yw[k][j] = __builtin_nontemporal_load((const u32x2*)(yr + lane * 4 + 256 * j)); }
;             }
;     ...
;                 const float* gate = R.mod + ((size_t)(R.lg * 9 + bb) * NMOD + R.gi) * DM;
; #pragma unroll
;                 for (int j = 0; j < 4; ++j) { const f32x4 g = *(const f32x4*)(gate + lane * 4 + 256 * j), gp = *(const f32x4*)(R.gpost + lane * 4 + 256 * j);
;                     v[k][j] = v[k][j] + g * (y[j] * rstd * gp); }
;             }
;             if (R.init || R.update) {
; #pragma unroll
;                 for (int j = 0; j < 4; ++j) __builtin_nontemporal_store(v[k][j], (f32x4*)(xrow[k] + lane * 4 + 256 * j));
;             }
;             if (R.norm_out) {
;                 float ss = 0.f;
; #pragma unroll
;                 for (int j = 0; j < 4; ++j) ss += (v[k][j][0] * v[k][j][0] + v[k][j][1] * v[k][j][1]) + (v[k][j][2] * v[k][j][2] + v[k][j][3] * v[k][j][3]);
;                 const float rstd = __builtin_amdgcn_rsqf(wave_sum(ss) * (1.0f / DM) + EPS);
;                 const float* shift = R.mod + ((size_t)(R.ln * 9 + bb) * NMOD + R.si) * DM; const float* scale = shift + DM;
.Lr2_slow_pfa:
	s_mov_b32 s6, s8
	s_ashr_i32 s7, s8, 31
	s_lshl_b64 s[6:7], s[6:7], 11
	v_lshl_add_u64 v[250:251], v[38:39], 0, s[6:7]
	v_lshl_add_u64 v[252:253], v[40:41], 0, s[6:7]
	s_mov_b64 s[6:7], s[52:53]
	s_add_i32 s72, s25, 0xffffff00
	s_cmp_lg_u64 s[6:7], 0
	s_cselect_b32 s27, s4, s49
	s_cselect_b32 s32, s5, s55
	s_cselect_b32 s37, 24, 20
	s_cselect_b32 s72, s72, s25
	s_mov_b32 s64, s9
	s_mov_b32 s65, 0
	s_lshl_b64 s[64:65], s[64:65], s37
	s_add_u32 s64, s27, s64
	s_addc_u32 s65, s32, s65
	s_lshl_b32 s72, s72, 12
	s_add_u32 s64, s64, s72
	s_addc_u32 s65, s65, 0
	s_cmp_lg_u64 s[6:7], 0
	s_cselect_b32 s22, s68, s70
	s_cselect_b32 s23, s69, s71
	s_add_u32 s22, s22, s64
	s_addc_u32 s23, s23, s65
	s_cmp_lg_u32 s99, 0
	s_cbranch_scc1 .Lr2_slow_pf
	s_mul_hi_i32 s26, s13, 0x78787879
	s_lshr_b32 s27, s26, 31
	s_ashr_i32 s26, s26, 11
	s_add_i32 s26, s26, s27
	s_mul_i32 s27, s26, 0xffffef00
	s_add_i32 s27, s13, s27
	s_cmpk_gt_i32 s27, 0xff
	s_cselect_b64 s[50:51], -1, 0
	s_cmp_lg_u64 s[50:51], 0
	s_cselect_b32 s85, s26, 8
	s_add_i32 s27, s85, s3
	s_mul_hi_i32 s32, s27, 0x6000
	s_mulk_i32 s27, 0x6000
	s_add_u32 s66, s34, s27
	s_addc_u32 s67, s35, s32
	s_add_u32 s66, s66, 0x2000
	s_addc_u32 s67, s67, 0
	s_add_i32 s27, s85, s3
	s_mul_hi_i32 s32, s27, 0x6000
	s_mulk_i32 s27, 0x6000
	s_add_u32 s38, s34, s27
	s_addc_u32 s39, s35, s32
	s_add_u32 s38, s38, 0x3000
	s_addc_u32 s39, s39, 0
	s_add_u32 s46, s38, 0x1000
	s_addc_u32 s47, s39, 0
	s_cmp_lg_u64 s[6:7], 0
	s_cselect_b32 s85, s9, 8
	s_add_i32 s27, s85, s3
	s_mul_hi_i32 s32, s27, 0x6000
	s_mulk_i32 s27, 0x6000
	s_add_u32 s10, s34, s27
	s_addc_u32 s11, s35, s32
	s_add_u32 s10, s10, 0x2000
	s_addc_u32 s11, s11, 0
	s_add_i32 s27, s85, s3
	s_mul_hi_i32 s32, s27, 0x6000
	s_mulk_i32 s27, 0x6000
	s_add_u32 s50, s34, s27
	s_addc_u32 s51, s35, s32
	s_add_u32 s50, s50, 0x3000
	s_addc_u32 s51, s51, 0
	s_add_u32 s52, s50, 0x1000
	s_addc_u32 s53, s51, 0
	s_and_b32 s72, s13, 7
	s_and_b32 s85, s72, 3
	s_lshl_b32 s85, s85, 10
	s_lshl_b32 s37, s72, 10
	s_add_i32 s37, s37, s93
	s_cmp_lt_u32 s72, 4
	s_cselect_b32 s6, s66, s38
	s_cselect_b32 s7, s67, s39
	s_cselect_b32 s8, s46, s10
	s_cselect_b32 s9, s47, s11
	s_cselect_b32 s26, s50, s52
	s_cselect_b32 s27, s51, s53
	s_add_u32 s6, s6, s85
	s_addc_u32 s7, s7, 0
	s_add_u32 s8, s8, s85
	s_addc_u32 s9, s9, 0
	s_add_u32 s26, s26, s85
	s_addc_u32 s27, s27, 0
	s_mov_b32 m0, s37
	s_nop 0
	global_load_lds_dwordx4 v160, s[6:7]
	s_add_i32 s37, s37, 0x2000
	s_mov_b32 m0, s37
	s_nop 0
	global_load_lds_dwordx4 v160, s[8:9]
	s_add_i32 s37, s37, 0x2000
	s_mov_b32 m0, s37
	s_nop 0
	global_load_lds_dwordx4 v160, s[26:27]
	global_load_dwordx4 v[16:19], v160, s[22:23] nt
	global_load_dwordx4 v[20:23], v160, s[22:23] offset:1024 nt
	global_load_dwordx4 v[24:27], v160, s[22:23] offset:2048 nt
	global_load_dwordx4 v[28:31], v160, s[22:23] offset:3072 nt
	global_load_dwordx2 v[62:63], v[250:251], off nt
	global_load_dwordx2 v[60:61], v[250:251], off offset:512 nt
	global_load_dwordx2 v[58:59], v[250:251], off offset:1024 nt
	global_load_dwordx2 v[56:57], v[250:251], off offset:1536 nt
	s_waitcnt vmcnt(8)
	s_branch .Lr2_slow_proc

;     __device__ __forceinline__ void init(int c_, unsigned* cnt_) { lat.init(NB * SEQ, FF2, 1, 0); c = c_; cnt = cnt_; }
; __device__ __forceinline__ void row_pass(const RowPass& R, int gw, int ngw, int lane) {
;     ...
;     for (int row0 = gw; row0 < M; row0 += NR * ngw) {
;         f32x4 v[NR][4]; u32x2 yw[NR][4]; bool act[NR]; float* xrow[NR]; int bbs[NR];
; #pragma unroll
;         for (int k = 0; k < NR; ++k) {
;             const int row = row0 + k * ngw;
;             const int rowc = row < M ? row : row0;
;             const int b = rowc / RPB, i = rowc - b * RPB; const bool isctx = i < CTXL;
;             act[k] = (row < M) && !(isctx && R.skip_ctx);
;             bbs[k] = isctx ? 8 : b;
;             xrow[k] = isctx ? R.xc + ((size_t)b * CTXL + i) * DM : R.out + ((size_t)b * SEQ + (i - CTXL)) * DM;
;             const float* src = R.init ? (isctx ? R.ctx_in + ((size_t)b * CTXL + i) * DM : R.x_in + ((size_t)b * SEQ + (i - CTXL)) * DM) : xrow[k];
;             if (act[k]) {
; #pragma unroll
;                 for (int j = 0; j < 4; ++j) v[k][j] = __builtin_nontemporal_load((const f32x4*)(src + lane * 4 + 256 * j));
;                 if (R.update) { const bf16* yr = R.Y + (size_t)rowc * DM;
; #pragma unroll
;                     for (int j = 0; j < 4; ++j) yw[k][j] = __builtin_nontemporal_load((const u32x2*)(yr + lane * 4 + 256 * j)); }
;             }
;     ...
;                 const float* gate = R.mod + ((size_t)(R.lg * 9 + bb) * NMOD + R.gi) * DM;
; #pragma unroll
;                 for (int j = 0; j < 4; ++j) { const f32x4 g = *(const f32x4*)(gate + lane * 4 + 256 * j), gp = *(const f32x4*)(R.gpost + lane * 4 + 256 * j);
;                     v[k][j] = v[k][j] + g * (y[j] * rstd * gp); }
;             }
;             if (R.init || R.update) {
; #pragma unroll
;                 for (int j = 0; j < 4; ++j) __builtin_nontemporal_store(v[k][j], (f32x4*)(xrow[k] + lane * 4 + 256 * j));
;             }
;             if (R.norm_out) {
;                 float ss = 0.f;
; #pragma unroll
;                 for (int j = 0; j < 4; ++j) ss += (v[k][j][0] * v[k][j][0] + v[k][j][1] * v[k][j][1]) + (v[k][j][2] * v[k][j][2] + v[k][j][3] * v[k][j][3]);
;                 const float rstd = __builtin_amdgcn_rsqf(wave_sum(ss) * (1.0f / DM) + EPS);
;                 const float* shift = R.mod + ((size_t)(R.ln * 9 + bb) * NMOD + R.si) * DM; const float* scale = shift + DM;
.LBB0_149:
	s_mul_hi_i32 s6, s19, 0x78787879
	s_lshr_b32 s7, s6, 31
	s_ashr_i32 s6, s6, 11
	s_add_i32 s6, s6, s7
	s_mul_i32 s7, s6, 0xffffef00
	s_add_i32 s7, s19, s7
	s_cmpk_gt_i32 s7, 0xff
	s_cselect_b64 s[50:51], -1, 0
	s_add_i32 s8, s44, s19
	s_cmp_lt_i32 s8, 0x8800
	s_cbranch_scc0 .Lr3_slow
	s_mul_hi_i32 s9, s8, 0x78787879
	s_lshr_b32 s25, s9, 31
	s_ashr_i32 s9, s9, 11
	s_add_i32 s9, s9, s25
	s_mul_i32 s25, s9, 0xffffef00
	s_add_i32 s25, s8, s25
	s_cmpk_gt_i32 s25, 0xff
	s_cselect_b64 s[52:53], -1, 0
	s_cmp_lg_u64 s[4:5], 0
	s_cbranch_scc0 .Lr3_slow_u
	v_lshlrev_b32_e32 v160, 2, v36
	s_add_i32 s72, s7, 0xffffff00
	s_cmp_lg_u64 s[50:51], 0
	s_cselect_b32 s27, s22, s49
	s_cselect_b32 s32, s23, s55
	s_cselect_b32 s37, 24, 20
	s_cselect_b32 s72, s72, s7
	s_mov_b32 s40, s6
	s_mov_b32 s41, 0
	s_lshl_b64 s[40:41], s[40:41], s37
	s_add_u32 s40, s27, s40
	s_addc_u32 s41, s32, s41
	s_lshl_b32 s72, s72, 12
	s_add_u32 s40, s40, s72
	s_addc_u32 s41, s41, 0
	s_cmp_lg_u32 s99, 0
	s_cbranch_scc1 .Lr3_slow_pfa
	global_load_dwordx4 v[12:15], v160, s[40:41] nt
	global_load_dwordx4 v[8:11], v160, s[40:41] offset:1024 nt
	global_load_dwordx4 v[4:7], v160, s[40:41] offset:2048 nt
	global_load_dwordx4 v[0:3], v160, s[40:41] offset:3072 nt
	global_load_dwordx2 v[54:55], v[46:47], off offset:-1536 nt
	global_load_dwordx2 v[52:53], v[46:47], off offset:-1024 nt
	global_load_dwordx2 v[50:51], v[46:47], off offset:-512 nt
	global_load_dwordx2 v[48:49], v[46:47], off nt
.Lr3_slow_pfa:
	s_mov_b32 s6, s8
	s_ashr_i32 s7, s8, 31
	s_lshl_b64 s[6:7], s[6:7], 11
	v_lshl_add_u64 v[250:251], v[38:39], 0, s[6:7]
	v_lshl_add_u64 v[252:253], v[40:41], 0, s[6:7]
	s_mov_b64 s[6:7], s[52:53]
	s_add_i32 s72, s25, 0xffffff00
	s_cmp_lg_u64 s[6:7], 0
	s_cselect_b32 s27, s22, s49
	s_cselect_b32 s32, s23, s55
	s_cselect_b32 s37, 24, 20
	s_cselect_b32 s72, s72, s25
	s_mov_b32 s64, s9
	s_mov_b32 s65, 0
	s_lshl_b64 s[64:65], s[64:65], s37
	s_add_u32 s64, s27, s64
	s_addc_u32 s65, s32, s65
	s_lshl_b32 s72, s72, 12
	s_add_u32 s64, s64, s72
	s_addc_u32 s65, s65, 0
	s_cmp_lg_u32 s99, 0
	s_cbranch_scc1 .Lr3_slow_pf
	s_mul_hi_i32 s26, s19, 0x78787879
	s_lshr_b32 s27, s26, 31
	s_ashr_i32 s26, s26, 11
	s_add_i32 s26, s26, s27
	s_mul_i32 s27, s26, 0xffffef00
	s_add_i32 s27, s19, s27
	s_cmpk_gt_i32 s27, 0xff
	s_cselect_b64 s[50:51], -1, 0
	s_cmp_lg_u64 s[50:51], 0
	s_cselect_b32 s85, s26, 8
	s_add_i32 s27, s85, s3
	s_mul_hi_i32 s32, s27, 0x6000
	s_mulk_i32 s27, 0x6000
	s_add_u32 s66, s34, s27
	s_addc_u32 s67, s35, s32
	s_add_u32 s66, s66, 0x5000
	s_addc_u32 s67, s67, 0
	s_add_i32 s27, s85, s13
	s_mul_hi_i32 s32, s27, 0x6000
	s_mulk_i32 s27, 0x6000
	s_add_u32 s38, s34, s27
	s_addc_u32 s39, s35, s32
	s_add_u32 s46, s38, 0x1000
	s_addc_u32 s47, s39, 0
	s_cmp_lg_u64 s[6:7], 0
	s_cselect_b32 s85, s9, 8
	s_add_i32 s27, s85, s3
	s_mul_hi_i32 s32, s27, 0x6000
	s_mulk_i32 s27, 0x6000
	s_add_u32 s10, s34, s27
	s_addc_u32 s11, s35, s32
	s_add_u32 s10, s10, 0x5000
	s_addc_u32 s11, s11, 0
	s_add_i32 s27, s85, s13
	s_mul_hi_i32 s32, s27, 0x6000
	s_mulk_i32 s27, 0x6000
	s_add_u32 s50, s34, s27
	s_addc_u32 s51, s35, s32
	s_add_u32 s52, s50, 0x1000
	s_addc_u32 s53, s51, 0
	s_and_b32 s72, s19, 7
	s_and_b32 s85, s72, 3
	s_lshl_b32 s85, s85, 10
	s_lshl_b32 s37, s72, 10
	s_add_i32 s37, s37, s93
	s_cmp_lt_u32 s72, 4
	s_cselect_b32 s6, s66, s38
	s_cselect_b32 s7, s67, s39
	s_cselect_b32 s8, s46, s10
	s_cselect_b32 s9, s47, s11
	s_cselect_b32 s26, s50, s52
	s_cselect_b32 s27, s51, s53
	s_add_u32 s6, s6, s85
	s_addc_u32 s7, s7, 0
	s_add_u32 s8, s8, s85
	s_addc_u32 s9, s9, 0
	s_add_u32 s26, s26, s85
	s_addc_u32 s27, s27, 0
	s_mov_b32 m0, s37
	s_nop 0
	global_load_lds_dwordx4 v160, s[6:7]
	s_add_i32 s37, s37, 0x2000
	s_mov_b32 m0, s37
	s_nop 0
	global_load_lds_dwordx4 v160, s[8:9]
	s_add_i32 s37, s37, 0x2000
	s_mov_b32 m0, s37
	s_nop 0
	global_load_lds_dwordx4 v160, s[26:27]
	global_load_dwordx4 v[16:19], v160, s[64:65] nt
	global_load_dwordx4 v[20:23], v160, s[64:65] offset:1024 nt
	global_load_dwordx4 v[24:27], v160, s[64:65] offset:2048 nt
	global_load_dwordx4 v[28:31], v160, s[64:65] offset:3072 nt
	global_load_dwordx2 v[62:63], v[250:251], off nt
	global_load_dwordx2 v[60:61], v[250:251], off offset:512 nt
	global_load_dwordx2 v[58:59], v[250:251], off offset:1024 nt
	global_load_dwordx2 v[56:57], v[250:251], off offset:1536 nt
	s_waitcnt vmcnt(8)
	s_branch .Lr3_slow_proc
